# scan phase now one workgroup barrier per chunk: operand images triple-buffered (staged two chunks ahead), Sr and score exchange double-buffered; +25600 B static LDS
# baseline (speedup 1.0000x reference)
; #define LAS __attribute__((address_space(3)))
; __device__ void scan_phase(LAS unsigned char* lds, const Params& p) {
;     const int tid = threadIdx.x, w = __builtin_amdgcn_readfirstlane(tid >> 6), lane = tid & 63, ln = lane & 15, lq = lane >> 4;
;     constexpr int QST = 136, VST = 36;
;     constexpr int OFF_KS = 17408, OFF_V = 34816, BUFB = 39424;
;     LAS bf16_t* Sr = (LAS bf16_t*)(lds + 2 * BUFB);
;     LAS float* scs = (LAS float*)(lds + 2 * BUFB + 9216);
;     bf16_t* O = (bf16_t*)p.out;
;     bf16_t* Odummy = (bf16_t*)(p.ws + WS_A) + (size_t)blockIdx.x * 64 * 512;
;     const float* RT = (const float*)(p.ws + WS_RT);
;     const int eb = w & 1, tb = w >> 1;
;     if (w >= 4) __builtin_amdgcn_s_setprio(1);
;     for (int item = blockIdx.x; item < 256; item += gridDim.x) {
;         const int seq = (item & 7) + 8 * (item >> 5), es = (item >> 3) & 3;
;         const int dir = seq & 1, h = (seq >> 1) & 3, b = seq >> 3;
;         const char* Qx = (const char*)((const bf16_t*)(p.ws + (dir ? WS_QB : WS_QF)) + h * 128);
;         const char* Kx = (const char*)((const bf16_t*)(p.ws + (dir ? WS_KB : WS_KF)) + h * 128);
;         const char* Vx = (const char*)((const bf16_t*)(p.ws + WS_V) + h * 128 + es * 32);
;         const char* Rx = (const char*)(RT + (size_t)dir * NCHUNK * 512 + h * 128);
;         const char* Tx = (const char*)(RT + (size_t)(2 + dir) * NCHUNK * 512 + h * 128);
;         const unsigned qoff0 = (unsigned)((dir ? 63 - (tid >> 4) : (tid >> 4)) * 1024 + (tid & 15) * 16), qstep = dir ? (unsigned)-32768 : 32768u;
;         const unsigned voff = (unsigned)((dir ? 63 - (tid >> 3) : (tid >> 3)) * 1024 + (tid & 7) * 8), roff = (unsigned)(tid & 127) * 4u;
;         f32x4 S[2] = {(f32x4){0.f, 0.f, 0.f, 0.f}, (f32x4){0.f, 0.f, 0.f, 0.f}};
;         float tailp = 0.f;
;         u32x4 k4A[2], k4B[2], k4C[2], k4D[2]; u32x4 q4A[2], q4B[2], q4C[2], q4D[2]; u32x2 v4A, v4B, v4C, v4D; float rvA, tlA, rvB, tlB, rvC, tlC, rvD, tlD;
;     ...
;         SCAN_LOAD(0, k4A, q4A, v4A, rvA, tlA); SCAN_LOAD(1, k4B, q4B, v4B, rvB, tlB); SCAN_LOAD(2, k4C, q4C, v4C, rvC, tlC); SCAN_LOAD(3, k4D, q4D, v4D, rvD, tlD);
;         SCAN_STAGE(0, k4A, q4A, v4A, rvA, tlA); SCAN_LOAD(4, k4A, q4A, v4A, rvA, tlA);
.LBB0_256:
	s_cmp_lt_i32 s72, 4
	s_cselect_b64 s[8:9], -1, 0
	s_waitcnt lgkmcnt(0)
	s_and_b64 s[38:39], s[8:9], s[6:7]
	s_andn2_b64 vcc, exec, s[38:39]
	s_cbranch_vccnz .LBB0_308
	v_lshrrev_b32_e32 v1, 6, v0
	s_nop 0
	v_readfirstlane_b32 s6, v1
	s_lshr_b32 s7, s6, 1
	s_and_b32 s8, s6, 1
	s_mov_b32 s9, s2
	s_load_dword s35, s[0:1], 0x98
	s_cmp_ge_u32 s7, 2
	s_cselect_b32 s11, 1, 0
	s_cmp_le_u32 s8, s7
	s_cselect_b32 s13, 1, 0
	s_add_u32 s3, s8, 2
	s_cmp_le_u32 s3, s7
	s_cselect_b32 s14, 1, 0
	v_and_b32_e32 v58, 15, v0
	v_bfe_u32 v59, v0, 4, 2
	v_lshrrev_b32_e32 v90, 2, v58
	v_and_b32_e32 v91, 3, v0
	v_and_b32_e32 v92, 63, v0
	v_lshlrev_b32_e32 v93, 2, v59
	v_add_u32_e32 v1, 0, v93
	v_cmp_le_u32_e64 s[94:95], v1, v58
	v_add_u32_e32 v1, 1, v93
	v_cmp_le_u32_e64 s[96:97], v1, v58
	v_add_u32_e32 v1, 2, v93
	v_cmp_le_u32_e64 s[98:99], v1, v58
	v_add_u32_e32 v1, 3, v93
	v_cmp_le_u32_e64 vcc, v1, v58
	s_cmp_eq_u32 s8, s7
	s_cselect_b64 s[76:77], s[94:95], -1
	s_cselect_b64 s[78:79], s[96:97], -1
	s_cselect_b64 s[80:81], s[98:99], -1
	s_cselect_b64 s[82:83], vcc, -1
	s_add_u32 s3, s8, 2
	s_cmp_eq_u32 s3, s7
	s_cselect_b64 s[84:85], s[94:95], -1
	s_cselect_b64 s[88:89], s[96:97], -1
	s_cselect_b64 s[90:91], s[98:99], -1
	s_cselect_b64 s[92:93], vcc, -1
	v_lshrrev_b32_e32 v1, 4, v0
	v_mul_u32_u24_e32 v60, 272, v1
	v_lshl_add_u32 v60, v58, 4, v60
	v_lshrrev_b32_e32 v1, 3, v0
	v_mul_u32_u24_e32 v63, 72, v1
	v_and_b32_e32 v1, 7, v0
	v_lshl_add_u32 v63, v1, 3, v63
	v_and_b32_e32 v1, 0x7f, v0
	v_lshlrev_b32_e32 v56, 2, v1
	s_cmp_lt_u32 s6, 2
	s_mov_b32 s4, 127488
	s_cselect_b32 s3, s4, 129024
	v_add_u32_e32 v78, s3, v56
	s_lshl_b32 s3, s7, 7
	s_add_u32 s3, s3, 127488
	v_lshl_add_u32 v79, v58, 2, s3
	s_mul_i32 s3, s7, 2304
	s_lshl_b32 s4, s8, 5
	s_add_u32 s3, s3, s4
	v_mul_u32_u24_e32 v1, 72, v58
	v_lshl_add_u32 v1, v59, 3, v1
	v_add_u32_e32 v1, s3, v1
	v_add_u32_e32 v80, 118272, v1
	v_add_u32_e32 v81, 131088, v1
	s_mul_i32 s3, s8, 4352
	v_mul_u32_u24_e32 v69, 272, v58
	v_lshl_add_u32 v69, v59, 4, v69
	v_add_u32_e32 v69, s3, v69
	s_mul_i32 s3, s7, 4352
	v_mul_u32_u24_e32 v66, 272, v58
	v_lshl_add_u32 v66, v59, 4, v66
	v_add_u32_e32 v66, s3, v66
	s_lshl_b32 s3, s7, 11
	v_lshl_add_u32 v1, v92, 4, s3
	s_lshl_b32 s4, s8, 3
	v_add_u32_e32 v86, 140304, v1
	v_add_u32_e32 v84, s4, v86
	v_add_u32_e32 v87, 148496, v1
	v_add_u32_e32 v85, s4, v87
	v_lshl_add_u32 v1, v59, 3, v90
	v_mul_u32_u24_e32 v1, 72, v1
	v_lshl_add_u32 v1, v91, 3, v1
	s_lshl_b32 s4, s8, 5
	v_add_u32_e32 v1, s4, v1
	v_add_u32_e32 v82, 118272, v1
	v_add_u32_e32 v83, 131088, v1
	v_lshl_add_u32 v1, v59, 2, v90
	v_mul_u32_u24_e32 v72, 72, v1
	v_lshl_add_u32 v72, v91, 3, v72
	v_add_u32_e32 v72, s4, v72
	v_mul_u32_u24_e32 v75, 272, v1
	v_lshl_add_u32 v75, v91, 3, v75
	s_lshl_b32 s3, s7, 6
	v_add_u32_e32 v75, s3, v75
	v_add_u32_e32 v61, 39424, v60
	v_add_u32_e32 v62, 78848, v60
	v_add_u32_e32 v64, 39424, v63
	v_add_u32_e32 v65, 78848, v63
	v_add_u32_e32 v67, 39424, v66
	v_add_u32_e32 v68, 78848, v66
	v_add_u32_e32 v70, 39424, v69
	v_add_u32_e32 v71, 78848, v69
	v_add_u32_e32 v73, 39424, v72
	v_add_u32_e32 v74, 78848, v72
	v_add_u32_e32 v76, 39424, v75
	v_add_u32_e32 v77, 78848, v75
	s_waitcnt lgkmcnt(0)
	s_cmp_gt_u32 s9, 0xff
	s_cbranch_scc1 .Lsc3_done
.Lsc3_item:
	s_and_b32 s10, s9, 1
	s_lshr_b32 s3, s9, 1
	s_and_b32 s3, s3, 3
	s_lshr_b32 s4, s9, 5
	s_lshr_b32 s5, s9, 3
	s_and_b32 s5, s5, 3
	s_cmp_eq_u32 s10, 0
	s_cselect_b32 s15, 1, -1
	s_cselect_b32 s64, 0, 3
	s_cselect_b32 s65, -4, 0x43
	s_lshl_b32 s16, s4, 2
	s_add_u32 s16, s16, 0x200
	s_lshl_b32 s17, s4, 6
	s_add_u32 s16, s16, s64
	s_add_i32 s17, s17, s65
	s_lshl_b32 s3, s3, 8
	s_lshl_b32 s5, s5, 6
	s_cmp_eq_u32 s10, 0
	s_mov_b32 s65, 0x5100000
	s_cselect_b32 s64, s65, 0x7300000
	s_add_u32 s64, s64, s3
	s_add_u32 s18, s70, s64
	s_addc_u32 s19, s71, 0
	s_cmp_eq_u32 s10, 0
	s_mov_b32 s65, 0x9500000
	s_cselect_b32 s64, s65, 0xb700000
	s_add_u32 s64, s64, s3
	s_add_u32 s20, s70, s64
	s_addc_u32 s21, s71, 0
	s_add_u32 s64, s3, s5
	s_add_u32 s65, s64, 0xd900000
	s_add_u32 s22, s70, s65
	s_addc_u32 s23, s71, 0
	s_lshl_b32 s65, s10, 25
	s_add_u32 s64, s64, s65
	s_add_u32 s28, s68, s64
	s_addc_u32 s29, s69, 0
	s_mul_i32 s64, s10, 0x110000
	s_lshl_b32 s65, s3, 1
	s_add_u32 s64, s64, s65
	s_add_u32 s64, s64, 0x15b00000
	s_add_u32 s24, s70, s64
	s_addc_u32 s25, s71, 0
	s_add_u32 s26, s24, 0x220000
	s_addc_u32 s27, s25, 0
	s_lshl_b32 s64, s9, 16
	s_add_u32 s64, s64, 0xd00000
	s_add_u32 s30, s70, s64
	s_addc_u32 s31, s71, 0
	s_mul_i32 s5, s10, 63
	s_lshl_b32 s3, s7, 4
	v_add_u32_e32 v1, s3, v58
	v_xor_b32_e32 v1, s5, v1
	v_lshlrev_b32_e32 v1, 10, v1
	s_lshl_b32 s3, s8, 5
	v_lshl_add_u32 v57, v59, 3, v1
	v_add_u32_e32 v57, s3, v57
	v_lshrrev_b32_e32 v1, 4, v0
	v_xor_b32_e32 v93, s5, v1
	v_lshlrev_b32_e32 v93, 10, v93
	v_lshl_add_u32 v53, v58, 4, v93
	v_add_u32_e32 v1, 32, v1
	v_xor_b32_e32 v93, s5, v1
	v_lshlrev_b32_e32 v93, 10, v93
	v_lshl_add_u32 v54, v58, 4, v93
	v_lshrrev_b32_e32 v1, 3, v0
	v_xor_b32_e32 v1, s5, v1
	v_lshlrev_b32_e32 v1, 10, v1
	v_and_b32_e32 v93, 7, v0
	v_lshl_add_u32 v55, v93, 3, v1
	v_mov_b32_e32 v42, 0
	v_mov_b32_e32 v43, 0
	v_mov_b32_e32 v44, 0
	v_mov_b32_e32 v45, 0
	v_mov_b32_e32 v46, 0
	v_mov_b32_e32 v47, 0
	v_mov_b32_e32 v48, 0
	v_mov_b32_e32 v49, 0
	v_mov_b32_e32 v52, 0
	v_mov_b32_e32 v160, 0
	v_mov_b32_e32 v161, 0
	v_mov_b32_e32 v162, 0
	v_mov_b32_e32 v163, 0
	v_mov_b32_e32 v176, 0
	v_mov_b32_e32 v177, 0
	s_mov_b32 s3, 0
	s_cmp_lt_u32 s3, 4
	s_cselect_b32 s4, s16, s17
	s_mul_i32 s5, s3, s15
	s_add_i32 s4, s4, s5
	s_lshl_b32 s5, s4, 16
	s_lshl_b32 s4, s4, 11
	s_add_u32 s40, s18, s5
	s_addc_u32 s41, s19, 0
	s_add_u32 s42, s20, s5
	s_addc_u32 s43, s21, 0
	s_add_u32 s44, s22, s5
	s_addc_u32 s45, s23, 0
	s_add_u32 s46, s24, s4
	s_addc_u32 s47, s25, 0
	s_add_u32 s50, s26, s4
	s_addc_u32 s51, s27, 0
	global_load_dwordx4 v[2:5], v53, s[40:41]
	global_load_dwordx4 v[6:9], v54, s[40:41]
	global_load_dwordx4 v[10:13], v53, s[42:43]
	global_load_dwordx4 v[14:17], v54, s[42:43]
	global_load_dwordx2 v[18:19], v55, s[44:45]
	global_load_dword v20, v56, s[46:47]
	global_load_dword v21, v56, s[50:51]
	s_mov_b32 s3, 1
	s_cmp_lt_u32 s3, 4
	s_cselect_b32 s4, s16, s17
	s_mul_i32 s5, s3, s15
	s_add_i32 s4, s4, s5
	s_lshl_b32 s5, s4, 16
	s_lshl_b32 s4, s4, 11
	s_add_u32 s40, s18, s5
	s_addc_u32 s41, s19, 0
	s_add_u32 s42, s20, s5
	s_addc_u32 s43, s21, 0
	s_add_u32 s44, s22, s5
	s_addc_u32 s45, s23, 0
	s_add_u32 s46, s24, s4
	s_addc_u32 s47, s25, 0
	s_add_u32 s50, s26, s4
	s_addc_u32 s51, s27, 0
	global_load_dwordx4 v[22:25], v53, s[40:41]
	global_load_dwordx4 v[26:29], v54, s[40:41]
	global_load_dwordx4 v[30:33], v53, s[42:43]
	global_load_dwordx4 v[34:37], v54, s[42:43]
	global_load_dwordx2 v[38:39], v55, s[44:45]
	global_load_dword v40, v56, s[46:47]
	global_load_dword v41, v56, s[50:51]
	s_waitcnt vmcnt(0)
; #define SCAN_BAR() asm volatile("s_waitcnt lgkmcnt(0)\n\ts_barrier" ::: "memory")
; __device__ void scan_phase(LAS unsigned char* lds, const Params& p) {
;     ...
;         SCAN_LOAD(0, k4A, q4A, v4A, rvA, tlA); SCAN_LOAD(1, k4B, q4B, v4B, rvB, tlB); SCAN_LOAD(2, k4C, q4C, v4C, rvC, tlC); SCAN_LOAD(3, k4D, q4D, v4D, rvD, tlD);
;         SCAN_STAGE(0, k4A, q4A, v4A, rvA, tlA); SCAN_LOAD(4, k4A, q4A, v4A, rvA, tlA);
;         SCAN_BAR();
; #pragma unroll 1
;         for (int n0 = 0; n0 < 68; n0 += 4) {
;             SCAN_STAGE(1, k4B, q4B, v4B, rvB, tlB); SCAN_LOAD(min(n0 + 5, 67), k4B, q4B, v4B, rvB, tlB); SCAN_MAT(0, n0); SCAN_BAR();
	ds_write_b128 v60, v[2:5] offset:0
	ds_write_b128 v60, v[6:9] offset:8704
	ds_write_b128 v60, v[10:13] offset:17408
	ds_write_b128 v60, v[14:17] offset:26112
	ds_write_b64 v63, v[18:19] offset:34816
	v_add_f32_e32 v92, v20, v52
	v_mul_f32_e32 v92, 0x3fb8aa3b, v92
	v_exp_f32_e32 v92, v92
	v_mov_b32_e32 v52, v21
	ds_write_b32 v78, v92 offset:0
	ds_write_b128 v61, v[22:25] offset:0
	ds_write_b128 v61, v[26:29] offset:8704
	ds_write_b128 v61, v[30:33] offset:17408
	ds_write_b128 v61, v[34:37] offset:26112
	ds_write_b64 v64, v[38:39] offset:34816
	v_add_f32_e32 v92, v40, v52
	v_mul_f32_e32 v92, 0x3fb8aa3b, v92
	v_exp_f32_e32 v92, v92
	v_mov_b32_e32 v52, v41
	ds_write_b32 v78, v92 offset:512
	s_mov_b32 s3, 2
	s_cmp_lt_u32 s3, 4
	s_cselect_b32 s4, s16, s17
	s_mul_i32 s5, s3, s15
	s_add_i32 s4, s4, s5
	s_lshl_b32 s5, s4, 16
	s_lshl_b32 s4, s4, 11
	s_add_u32 s40, s18, s5
	s_addc_u32 s41, s19, 0
	s_add_u32 s42, s20, s5
	s_addc_u32 s43, s21, 0
	s_add_u32 s44, s22, s5
	s_addc_u32 s45, s23, 0
	s_add_u32 s46, s24, s4
	s_addc_u32 s47, s25, 0
	s_add_u32 s50, s26, s4
	s_addc_u32 s51, s27, 0
	global_load_dwordx4 v[2:5], v53, s[40:41]
	global_load_dwordx4 v[6:9], v54, s[40:41]
	global_load_dwordx4 v[10:13], v53, s[42:43]
	global_load_dwordx4 v[14:17], v54, s[42:43]
	global_load_dwordx2 v[18:19], v55, s[44:45]
	global_load_dword v20, v56, s[46:47]
	global_load_dword v21, v56, s[50:51]
	global_store_dwordx2 v57, v[176:177], s[30:31]
	s_waitcnt lgkmcnt(0)
	s_barrier
	s_mov_b32 s34, 0
.Lsc3_loop:
	ds_read_b32 v50, v79 offset:0
	ds_read_b32 v51, v79 offset:64
	ds_read_b128 v[96:99], v66 offset:0
	ds_read_b128 v[100:103], v66 offset:64
	ds_read_b128 v[104:107], v66 offset:128
	ds_read_b128 v[108:111], v66 offset:192
	s_cmp_eq_u32 s13, 0
	s_cbranch_scc1 .Lsc3_nox_0
	ds_read_b128 v[112:115], v69 offset:17408
	ds_read_b128 v[116:119], v69 offset:17472
	ds_read_b128 v[120:123], v69 offset:17536
	ds_read_b128 v[124:127], v69 offset:17600
.Lsc3_nox_0:
	s_cmp_eq_u32 s14, 0
	s_cbranch_scc1 .Lsc3_noy_0
	ds_read_b128 v[128:131], v69 offset:26112
	ds_read_b128 v[132:135], v69 offset:26176
	ds_read_b128 v[136:139], v69 offset:26240
	ds_read_b128 v[140:143], v69 offset:26304
.Lsc3_noy_0:
	s_add_u32 s3, s34, 3
	s_min_u32 s3, s3, 67
	s_cmp_lt_u32 s3, 4
	s_cselect_b32 s4, s16, s17
	s_mul_i32 s5, s3, s15
	s_add_i32 s4, s4, s5
	s_lshl_b32 s5, s4, 16
	s_lshl_b32 s4, s4, 11
	s_add_u32 s40, s18, s5
	s_addc_u32 s41, s19, 0
	s_add_u32 s42, s20, s5
	s_addc_u32 s43, s21, 0
	s_add_u32 s44, s22, s5
	s_addc_u32 s45, s23, 0
	s_add_u32 s46, s24, s4
	s_addc_u32 s47, s25, 0
	s_add_u32 s50, s26, s4
	s_addc_u32 s51, s27, 0
	global_load_dwordx4 v[22:25], v53, s[40:41]
	global_load_dwordx4 v[26:29], v54, s[40:41]
	global_load_dwordx4 v[30:33], v53, s[42:43]
	global_load_dwordx4 v[34:37], v54, s[42:43]
	global_load_dwordx2 v[38:39], v55, s[44:45]
	global_load_dword v40, v56, s[46:47]
	global_load_dword v41, v56, s[50:51]
	s_waitcnt lgkmcnt(0)
	s_cmp_eq_u32 s13, 0
	s_cbranch_scc1 .Lsc3_nox2_0
	v_mfma_f32_16x16x32_bf16 v[152:155], v[112:115], v[96:99], 0
	v_mfma_f32_16x16x32_bf16 v[152:155], v[116:119], v[100:103], v[152:155]
	v_mfma_f32_16x16x32_bf16 v[152:155], v[120:123], v[104:107], v[152:155]
	v_mfma_f32_16x16x32_bf16 v[152:155], v[124:127], v[108:111], v[152:155]
.Lsc3_nox2_0:
	s_cmp_eq_u32 s14, 0
	s_cbranch_scc1 .Lsc3_noy2_0
	v_mfma_f32_16x16x32_bf16 v[156:159], v[128:131], v[96:99], 0
	v_mfma_f32_16x16x32_bf16 v[156:159], v[132:135], v[100:103], v[156:159]
	v_mfma_f32_16x16x32_bf16 v[156:159], v[136:139], v[104:107], v[156:159]
	v_mfma_f32_16x16x32_bf16 v[156:159], v[140:143], v[108:111], v[156:159]
.Lsc3_noy2_0:
	v_mul_f32_e32 v42, v42, v50
	v_mul_f32_e32 v43, v43, v50
	v_mul_f32_e32 v44, v44, v50
	v_mul_f32_e32 v45, v45, v50
	v_mul_f32_e32 v46, v46, v51
	v_mul_f32_e32 v47, v47, v51
	v_mul_f32_e32 v48, v48, v51
	v_mul_f32_e32 v49, v49, v51
	v_cvt_pk_bf16_f32 v88, v42, v43
	v_cvt_pk_bf16_f32 v89, v44, v45
	v_cvt_pk_bf16_f32 v90, v46, v47
	v_cvt_pk_bf16_f32 v91, v48, v49
	ds_write_b64 v80, v[88:89]
	ds_write_b64 v80, v[90:91] offset:1152
	s_cmp_eq_u32 s13, 0
	s_cbranch_scc1 .Lsc3_nox3_0
	v_cndmask_b32_e64 v152, 0, v152, s[76:77]
	v_cndmask_b32_e64 v153, 0, v153, s[78:79]
	v_cndmask_b32_e64 v154, 0, v154, s[80:81]
	v_cndmask_b32_e64 v155, 0, v155, s[82:83]
	v_cvt_pk_bf16_f32 v160, v152, v153
	v_cvt_pk_bf16_f32 v161, v154, v155
.Lsc3_nox3_0:
	s_cmp_eq_u32 s14, 0
	s_cbranch_scc1 .Lsc3_noy3_0
	v_cndmask_b32_e64 v156, 0, v156, s[84:85]
	v_cndmask_b32_e64 v157, 0, v157, s[88:89]
	v_cndmask_b32_e64 v158, 0, v158, s[90:91]
	v_cndmask_b32_e64 v159, 0, v159, s[92:93]
	v_cvt_pk_bf16_f32 v162, v156, v157
	v_cvt_pk_bf16_f32 v163, v158, v159
.Lsc3_noy3_0:
	ds_write_b64 v84, v[160:161]
	ds_write_b64 v84, v[162:163] offset:1024
	s_waitcnt lgkmcnt(0)
	s_barrier
	ds_read_b64_tr_b16 v[112:113], v82 offset:0
	ds_read_b64_tr_b16 v[114:115], v82 offset:288
	ds_read_b64_tr_b16 v[116:117], v82 offset:2304
	ds_read_b64_tr_b16 v[118:119], v82 offset:2592
	ds_read_b64_tr_b16 v[120:121], v82 offset:4608
	ds_read_b64_tr_b16 v[122:123], v82 offset:4896
	ds_read_b64_tr_b16 v[124:125], v82 offset:6912
	ds_read_b64_tr_b16 v[126:127], v82 offset:7200
	ds_read_b64_tr_b16 v[128:129], v72 offset:34816
	ds_read_b64_tr_b16 v[130:131], v72 offset:35968
	ds_read_b64_tr_b16 v[132:133], v72 offset:37120
	ds_read_b64_tr_b16 v[134:135], v72 offset:38272
	ds_read_b128 v[164:167], v86
	ds_read_b128 v[168:171], v86 offset:1024
	s_waitcnt lgkmcnt(12)
	v_mfma_f32_16x16x32_bf16 v[172:175], v[112:115], v[96:99], 0
	ds_read_b64_tr_b16 v[136:137], v75 offset:17408
	ds_read_b64_tr_b16 v[138:139], v75 offset:21760
	s_waitcnt lgkmcnt(12)
	v_mfma_f32_16x16x32_bf16 v[172:175], v[116:119], v[100:103], v[172:175]
	ds_read_b64_tr_b16 v[140:141], v75 offset:17440
	ds_read_b64_tr_b16 v[142:143], v75 offset:21792
	s_waitcnt lgkmcnt(12)
	v_mfma_f32_16x16x32_bf16 v[172:175], v[120:123], v[104:107], v[172:175]
	ds_read_b64_tr_b16 v[144:145], v75 offset:26112
	ds_read_b64_tr_b16 v[146:147], v75 offset:30464
	s_waitcnt lgkmcnt(12)
	v_mfma_f32_16x16x32_bf16 v[172:175], v[124:127], v[108:111], v[172:175]
	ds_read_b64_tr_b16 v[148:149], v75 offset:26144
	ds_read_b64_tr_b16 v[150:151], v75 offset:30496
	s_waitcnt lgkmcnt(9)
	v_mfma_f32_16x16x32_bf16 v[172:175], v[128:131], v[164:167], v[172:175]
	s_waitcnt vmcnt(8)
	ds_write_b128 v62, v[2:5] offset:0
	ds_write_b128 v62, v[6:9] offset:8704
	ds_write_b128 v62, v[10:13] offset:17408
	ds_write_b128 v62, v[14:17] offset:26112
	ds_write_b64 v65, v[18:19] offset:34816
	v_add_f32_e32 v92, v20, v52
	v_mul_f32_e32 v92, 0x3fb8aa3b, v92
	v_exp_f32_e32 v92, v92
	v_mov_b32_e32 v52, v21
	ds_write_b32 v78, v92 offset:1024
	s_waitcnt lgkmcnt(14)
	s_cmp_eq_u32 s11, 0
	s_cbranch_scc1 .Lsc3_nopv1_0
	v_mfma_f32_16x16x32_bf16 v[172:175], v[132:135], v[168:171], v[172:175]
.Lsc3_nopv1_0:
	s_waitcnt lgkmcnt(12)
	v_mfma_f32_16x16x32_bf16 v[42:45], v[128:131], v[136:139], v[42:45]
	s_waitcnt lgkmcnt(10)
	v_mfma_f32_16x16x32_bf16 v[46:49], v[128:131], v[140:143], v[46:49]
	s_waitcnt lgkmcnt(8)
	v_mfma_f32_16x16x32_bf16 v[42:45], v[132:135], v[144:147], v[42:45]
	s_waitcnt lgkmcnt(6)
	v_mfma_f32_16x16x32_bf16 v[46:49], v[132:135], v[148:151], v[46:49]
	s_add_u32 s3, s34, 0
	s_cmp_lt_u32 s3, 4
	s_cselect_b32 s4, s16, s17
	s_mul_i32 s5, s3, s15
	s_add_i32 s4, s4, s5
	s_lshl_b32 s4, s4, 16
	s_add_u32 s64, s28, s4
	s_addc_u32 s65, s29, 0
	s_cmp_eq_u32 s34, 0
	s_cselect_b32 s64, s30, s64
	s_cselect_b32 s65, s31, s65
	v_cvt_pk_bf16_f32 v176, v172, v173
	v_cvt_pk_bf16_f32 v177, v174, v175
	global_store_dwordx2 v57, v[176:177], s[64:65]
	s_waitcnt lgkmcnt(0)
	ds_read_b32 v50, v79 offset:512
	ds_read_b32 v51, v79 offset:576
	ds_read_b128 v[96:99], v67 offset:0
	ds_read_b128 v[100:103], v67 offset:64
	ds_read_b128 v[104:107], v67 offset:128
	ds_read_b128 v[108:111], v67 offset:192
	s_cmp_eq_u32 s13, 0
	s_cbranch_scc1 .Lsc3_nox_1
	ds_read_b128 v[112:115], v70 offset:17408
	ds_read_b128 v[116:119], v70 offset:17472
	ds_read_b128 v[120:123], v70 offset:17536
	ds_read_b128 v[124:127], v70 offset:17600
.Lsc3_nox_1:
	s_cmp_eq_u32 s14, 0
	s_cbranch_scc1 .Lsc3_noy_1
	ds_read_b128 v[128:131], v70 offset:26112
	ds_read_b128 v[132:135], v70 offset:26176
	ds_read_b128 v[136:139], v70 offset:26240
	ds_read_b128 v[140:143], v70 offset:26304
.Lsc3_noy_1:
	s_add_u32 s3, s34, 4
	s_min_u32 s3, s3, 67
	s_cmp_lt_u32 s3, 4
	s_cselect_b32 s4, s16, s17
	s_mul_i32 s5, s3, s15
	s_add_i32 s4, s4, s5
	s_lshl_b32 s5, s4, 16
	s_lshl_b32 s4, s4, 11
	s_add_u32 s40, s18, s5
	s_addc_u32 s41, s19, 0
	s_add_u32 s42, s20, s5
	s_addc_u32 s43, s21, 0
	s_add_u32 s44, s22, s5
	s_addc_u32 s45, s23, 0
	s_add_u32 s46, s24, s4
	s_addc_u32 s47, s25, 0
	s_add_u32 s50, s26, s4
	s_addc_u32 s51, s27, 0
	global_load_dwordx4 v[2:5], v53, s[40:41]
	global_load_dwordx4 v[6:9], v54, s[40:41]
	global_load_dwordx4 v[10:13], v53, s[42:43]
	global_load_dwordx4 v[14:17], v54, s[42:43]
	global_load_dwordx2 v[18:19], v55, s[44:45]
	global_load_dword v20, v56, s[46:47]
	global_load_dword v21, v56, s[50:51]
	s_waitcnt lgkmcnt(0)
	s_cmp_eq_u32 s13, 0
	s_cbranch_scc1 .Lsc3_nox2_1
	v_mfma_f32_16x16x32_bf16 v[152:155], v[112:115], v[96:99], 0
	v_mfma_f32_16x16x32_bf16 v[152:155], v[116:119], v[100:103], v[152:155]
	v_mfma_f32_16x16x32_bf16 v[152:155], v[120:123], v[104:107], v[152:155]
	v_mfma_f32_16x16x32_bf16 v[152:155], v[124:127], v[108:111], v[152:155]

.Lsc3_noy2_1:
	v_mul_f32_e32 v42, v42, v50
	v_mul_f32_e32 v43, v43, v50
	v_mul_f32_e32 v44, v44, v50
	v_mul_f32_e32 v45, v45, v50
	v_mul_f32_e32 v46, v46, v51
	v_mul_f32_e32 v47, v47, v51
	v_mul_f32_e32 v48, v48, v51
	v_mul_f32_e32 v49, v49, v51
	v_cvt_pk_bf16_f32 v88, v42, v43
	v_cvt_pk_bf16_f32 v89, v44, v45
	v_cvt_pk_bf16_f32 v90, v46, v47
	v_cvt_pk_bf16_f32 v91, v48, v49
	ds_write_b64 v81, v[88:89]
	ds_write_b64 v81, v[90:91] offset:1152
	s_cmp_eq_u32 s13, 0
	s_cbranch_scc1 .Lsc3_nox3_1
	v_cndmask_b32_e64 v152, 0, v152, s[76:77]
	v_cndmask_b32_e64 v153, 0, v153, s[78:79]
	v_cndmask_b32_e64 v154, 0, v154, s[80:81]
	v_cndmask_b32_e64 v155, 0, v155, s[82:83]
	v_cvt_pk_bf16_f32 v160, v152, v153
	v_cvt_pk_bf16_f32 v161, v154, v155

.Lsc3_noy3_1:
	ds_write_b64 v85, v[160:161]
	ds_write_b64 v85, v[162:163] offset:1024
	s_waitcnt lgkmcnt(0)
	s_barrier
	ds_read_b64_tr_b16 v[112:113], v83 offset:0
	ds_read_b64_tr_b16 v[114:115], v83 offset:288
	ds_read_b64_tr_b16 v[116:117], v83 offset:2304
	ds_read_b64_tr_b16 v[118:119], v83 offset:2592
	ds_read_b64_tr_b16 v[120:121], v83 offset:4608
	ds_read_b64_tr_b16 v[122:123], v83 offset:4896
	ds_read_b64_tr_b16 v[124:125], v83 offset:6912
	ds_read_b64_tr_b16 v[126:127], v83 offset:7200
	ds_read_b64_tr_b16 v[128:129], v73 offset:34816
	ds_read_b64_tr_b16 v[130:131], v73 offset:35968
	ds_read_b64_tr_b16 v[132:133], v73 offset:37120
	ds_read_b64_tr_b16 v[134:135], v73 offset:38272
	ds_read_b128 v[164:167], v87
	ds_read_b128 v[168:171], v87 offset:1024
	s_waitcnt lgkmcnt(12)
	v_mfma_f32_16x16x32_bf16 v[172:175], v[112:115], v[96:99], 0
	ds_read_b64_tr_b16 v[136:137], v76 offset:17408
	ds_read_b64_tr_b16 v[138:139], v76 offset:21760
	s_waitcnt lgkmcnt(12)
	v_mfma_f32_16x16x32_bf16 v[172:175], v[116:119], v[100:103], v[172:175]
	ds_read_b64_tr_b16 v[140:141], v76 offset:17440
	ds_read_b64_tr_b16 v[142:143], v76 offset:21792
	s_waitcnt lgkmcnt(12)
	v_mfma_f32_16x16x32_bf16 v[172:175], v[120:123], v[104:107], v[172:175]
	ds_read_b64_tr_b16 v[144:145], v76 offset:26112
	ds_read_b64_tr_b16 v[146:147], v76 offset:30464
	s_waitcnt lgkmcnt(12)
	v_mfma_f32_16x16x32_bf16 v[172:175], v[124:127], v[108:111], v[172:175]
	ds_read_b64_tr_b16 v[148:149], v76 offset:26144
	ds_read_b64_tr_b16 v[150:151], v76 offset:30496
	s_waitcnt lgkmcnt(9)
	v_mfma_f32_16x16x32_bf16 v[172:175], v[128:131], v[164:167], v[172:175]
	s_waitcnt vmcnt(8)
	ds_write_b128 v60, v[22:25] offset:0
	ds_write_b128 v60, v[26:29] offset:8704
	ds_write_b128 v60, v[30:33] offset:17408
	ds_write_b128 v60, v[34:37] offset:26112
	ds_write_b64 v63, v[38:39] offset:34816
	v_add_f32_e32 v92, v40, v52
	v_mul_f32_e32 v92, 0x3fb8aa3b, v92
	v_exp_f32_e32 v92, v92
	v_mov_b32_e32 v52, v41
	ds_write_b32 v78, v92 offset:0
	s_waitcnt lgkmcnt(14)
	s_cmp_eq_u32 s11, 0
	s_cbranch_scc1 .Lsc3_nopv1_1
	v_mfma_f32_16x16x32_bf16 v[172:175], v[132:135], v[168:171], v[172:175]
.Lsc3_nopv1_1:
	s_waitcnt lgkmcnt(12)
	v_mfma_f32_16x16x32_bf16 v[42:45], v[128:131], v[136:139], v[42:45]
	s_waitcnt lgkmcnt(10)
	v_mfma_f32_16x16x32_bf16 v[46:49], v[128:131], v[140:143], v[46:49]
	s_waitcnt lgkmcnt(8)
	v_mfma_f32_16x16x32_bf16 v[42:45], v[132:135], v[144:147], v[42:45]
	s_waitcnt lgkmcnt(6)
	v_mfma_f32_16x16x32_bf16 v[46:49], v[132:135], v[148:151], v[46:49]
	s_add_u32 s3, s34, 1
	s_cmp_lt_u32 s3, 4
	s_cselect_b32 s4, s16, s17
	s_mul_i32 s5, s3, s15
	s_add_i32 s4, s4, s5
	s_lshl_b32 s4, s4, 16
	s_add_u32 s64, s28, s4
	s_addc_u32 s65, s29, 0
	s_cmp_eq_u32 s34, 0
	s_cselect_b32 s64, s30, s64
	s_cselect_b32 s65, s31, s65
	v_cvt_pk_bf16_f32 v176, v172, v173
	v_cvt_pk_bf16_f32 v177, v174, v175
	global_store_dwordx2 v57, v[176:177], s[64:65]
	s_waitcnt lgkmcnt(0)
	ds_read_b32 v50, v79 offset:1024
	ds_read_b32 v51, v79 offset:1088
	ds_read_b128 v[96:99], v68 offset:0
	ds_read_b128 v[100:103], v68 offset:64
	ds_read_b128 v[104:107], v68 offset:128
	ds_read_b128 v[108:111], v68 offset:192
	s_cmp_eq_u32 s13, 0
	s_cbranch_scc1 .Lsc3_nox_2
	ds_read_b128 v[112:115], v71 offset:17408
	ds_read_b128 v[116:119], v71 offset:17472
	ds_read_b128 v[120:123], v71 offset:17536
	ds_read_b128 v[124:127], v71 offset:17600
.Lsc3_nox_2:
	s_cmp_eq_u32 s14, 0
	s_cbranch_scc1 .Lsc3_noy_2
	ds_read_b128 v[128:131], v71 offset:26112
	ds_read_b128 v[132:135], v71 offset:26176
	ds_read_b128 v[136:139], v71 offset:26240
	ds_read_b128 v[140:143], v71 offset:26304
.Lsc3_noy_2:
	s_add_u32 s3, s34, 5
	s_min_u32 s3, s3, 67
	s_cmp_lt_u32 s3, 4
	s_cselect_b32 s4, s16, s17
	s_mul_i32 s5, s3, s15
	s_add_i32 s4, s4, s5
	s_lshl_b32 s5, s4, 16
	s_lshl_b32 s4, s4, 11
	s_add_u32 s40, s18, s5
	s_addc_u32 s41, s19, 0
	s_add_u32 s42, s20, s5
	s_addc_u32 s43, s21, 0
	s_add_u32 s44, s22, s5
	s_addc_u32 s45, s23, 0
	s_add_u32 s46, s24, s4
	s_addc_u32 s47, s25, 0
	s_add_u32 s50, s26, s4
	s_addc_u32 s51, s27, 0
	global_load_dwordx4 v[22:25], v53, s[40:41]
	global_load_dwordx4 v[26:29], v54, s[40:41]
	global_load_dwordx4 v[30:33], v53, s[42:43]
	global_load_dwordx4 v[34:37], v54, s[42:43]
	global_load_dwordx2 v[38:39], v55, s[44:45]
	global_load_dword v40, v56, s[46:47]
	global_load_dword v41, v56, s[50:51]
	s_waitcnt lgkmcnt(0)
	s_cmp_eq_u32 s13, 0
	s_cbranch_scc1 .Lsc3_nox2_2
	v_mfma_f32_16x16x32_bf16 v[152:155], v[112:115], v[96:99], 0
	v_mfma_f32_16x16x32_bf16 v[152:155], v[116:119], v[100:103], v[152:155]
	v_mfma_f32_16x16x32_bf16 v[152:155], v[120:123], v[104:107], v[152:155]
	v_mfma_f32_16x16x32_bf16 v[152:155], v[124:127], v[108:111], v[152:155]

.Lsc3_noy3_2:
	ds_write_b64 v84, v[160:161]
	ds_write_b64 v84, v[162:163] offset:1024
	s_waitcnt lgkmcnt(0)
	s_barrier
	ds_read_b64_tr_b16 v[112:113], v82 offset:0
	ds_read_b64_tr_b16 v[114:115], v82 offset:288
	ds_read_b64_tr_b16 v[116:117], v82 offset:2304
	ds_read_b64_tr_b16 v[118:119], v82 offset:2592
	ds_read_b64_tr_b16 v[120:121], v82 offset:4608
	ds_read_b64_tr_b16 v[122:123], v82 offset:4896
	ds_read_b64_tr_b16 v[124:125], v82 offset:6912
	ds_read_b64_tr_b16 v[126:127], v82 offset:7200
	ds_read_b64_tr_b16 v[128:129], v74 offset:34816
	ds_read_b64_tr_b16 v[130:131], v74 offset:35968
	ds_read_b64_tr_b16 v[132:133], v74 offset:37120
	ds_read_b64_tr_b16 v[134:135], v74 offset:38272
	ds_read_b128 v[164:167], v86
	ds_read_b128 v[168:171], v86 offset:1024
	s_waitcnt lgkmcnt(12)
	v_mfma_f32_16x16x32_bf16 v[172:175], v[112:115], v[96:99], 0
	ds_read_b64_tr_b16 v[136:137], v77 offset:17408
	ds_read_b64_tr_b16 v[138:139], v77 offset:21760
	s_waitcnt lgkmcnt(12)
	v_mfma_f32_16x16x32_bf16 v[172:175], v[116:119], v[100:103], v[172:175]
	ds_read_b64_tr_b16 v[140:141], v77 offset:17440
	ds_read_b64_tr_b16 v[142:143], v77 offset:21792
	s_waitcnt lgkmcnt(12)
	v_mfma_f32_16x16x32_bf16 v[172:175], v[120:123], v[104:107], v[172:175]
	ds_read_b64_tr_b16 v[144:145], v77 offset:26112
	ds_read_b64_tr_b16 v[146:147], v77 offset:30464
	s_waitcnt lgkmcnt(12)
	v_mfma_f32_16x16x32_bf16 v[172:175], v[124:127], v[108:111], v[172:175]
	ds_read_b64_tr_b16 v[148:149], v77 offset:26144
	ds_read_b64_tr_b16 v[150:151], v77 offset:30496
	s_waitcnt lgkmcnt(9)
	v_mfma_f32_16x16x32_bf16 v[172:175], v[128:131], v[164:167], v[172:175]
	s_waitcnt vmcnt(8)
	ds_write_b128 v61, v[2:5] offset:0
	ds_write_b128 v61, v[6:9] offset:8704
	ds_write_b128 v61, v[10:13] offset:17408
	ds_write_b128 v61, v[14:17] offset:26112
	ds_write_b64 v64, v[18:19] offset:34816
	v_add_f32_e32 v92, v20, v52
	v_mul_f32_e32 v92, 0x3fb8aa3b, v92
	v_exp_f32_e32 v92, v92
	v_mov_b32_e32 v52, v21
	ds_write_b32 v78, v92 offset:512
	s_waitcnt lgkmcnt(14)
	s_cmp_eq_u32 s11, 0
	s_cbranch_scc1 .Lsc3_nopv1_2
	v_mfma_f32_16x16x32_bf16 v[172:175], v[132:135], v[168:171], v[172:175]
.Lsc3_nopv1_2:
	s_waitcnt lgkmcnt(12)
	v_mfma_f32_16x16x32_bf16 v[42:45], v[128:131], v[136:139], v[42:45]
	s_waitcnt lgkmcnt(10)
	v_mfma_f32_16x16x32_bf16 v[46:49], v[128:131], v[140:143], v[46:49]
	s_waitcnt lgkmcnt(8)
	v_mfma_f32_16x16x32_bf16 v[42:45], v[132:135], v[144:147], v[42:45]
	s_waitcnt lgkmcnt(6)
	v_mfma_f32_16x16x32_bf16 v[46:49], v[132:135], v[148:151], v[46:49]
	s_add_u32 s3, s34, 2
	s_cmp_lt_u32 s3, 4
	s_cselect_b32 s4, s16, s17
	s_mul_i32 s5, s3, s15
	s_add_i32 s4, s4, s5
	s_lshl_b32 s4, s4, 16
	s_add_u32 s64, s28, s4
	s_addc_u32 s65, s29, 0
	s_cmp_eq_u32 s34, 0
	s_cselect_b32 s64, s30, s64
	s_cselect_b32 s65, s31, s65
	v_cvt_pk_bf16_f32 v176, v172, v173
	v_cvt_pk_bf16_f32 v177, v174, v175
	global_store_dwordx2 v57, v[176:177], s[64:65]
	s_waitcnt lgkmcnt(0)
	ds_read_b32 v50, v79 offset:0
	ds_read_b32 v51, v79 offset:64
	ds_read_b128 v[96:99], v66 offset:0
	ds_read_b128 v[100:103], v66 offset:64
	ds_read_b128 v[104:107], v66 offset:128
	ds_read_b128 v[108:111], v66 offset:192
	s_cmp_eq_u32 s13, 0
	s_cbranch_scc1 .Lsc3_nox_3
	ds_read_b128 v[112:115], v69 offset:17408
	ds_read_b128 v[116:119], v69 offset:17472
	ds_read_b128 v[120:123], v69 offset:17536
	ds_read_b128 v[124:127], v69 offset:17600

.Lsc3_noy_3:
	s_add_u32 s3, s34, 6
	s_min_u32 s3, s3, 67
	s_cmp_lt_u32 s3, 4
	s_cselect_b32 s4, s16, s17
	s_mul_i32 s5, s3, s15
	s_add_i32 s4, s4, s5
	s_lshl_b32 s5, s4, 16
	s_lshl_b32 s4, s4, 11
	s_add_u32 s40, s18, s5
	s_addc_u32 s41, s19, 0
	s_add_u32 s42, s20, s5
	s_addc_u32 s43, s21, 0
	s_add_u32 s44, s22, s5
	s_addc_u32 s45, s23, 0
	s_add_u32 s46, s24, s4
	s_addc_u32 s47, s25, 0
	s_add_u32 s50, s26, s4
	s_addc_u32 s51, s27, 0
	global_load_dwordx4 v[2:5], v53, s[40:41]
	global_load_dwordx4 v[6:9], v54, s[40:41]
	global_load_dwordx4 v[10:13], v53, s[42:43]
	global_load_dwordx4 v[14:17], v54, s[42:43]
	global_load_dwordx2 v[18:19], v55, s[44:45]
	global_load_dword v20, v56, s[46:47]
	global_load_dword v21, v56, s[50:51]
	s_waitcnt lgkmcnt(0)
	s_cmp_eq_u32 s13, 0
	s_cbranch_scc1 .Lsc3_nox2_3
	v_mfma_f32_16x16x32_bf16 v[152:155], v[112:115], v[96:99], 0
	v_mfma_f32_16x16x32_bf16 v[152:155], v[116:119], v[100:103], v[152:155]
	v_mfma_f32_16x16x32_bf16 v[152:155], v[120:123], v[104:107], v[152:155]
	v_mfma_f32_16x16x32_bf16 v[152:155], v[124:127], v[108:111], v[152:155]

.Lsc3_noy3_3:
	ds_write_b64 v85, v[160:161]
	ds_write_b64 v85, v[162:163] offset:1024
	s_waitcnt lgkmcnt(0)
	s_barrier
	ds_read_b64_tr_b16 v[112:113], v83 offset:0
	ds_read_b64_tr_b16 v[114:115], v83 offset:288
	ds_read_b64_tr_b16 v[116:117], v83 offset:2304
	ds_read_b64_tr_b16 v[118:119], v83 offset:2592
	ds_read_b64_tr_b16 v[120:121], v83 offset:4608
	ds_read_b64_tr_b16 v[122:123], v83 offset:4896
	ds_read_b64_tr_b16 v[124:125], v83 offset:6912
	ds_read_b64_tr_b16 v[126:127], v83 offset:7200
	ds_read_b64_tr_b16 v[128:129], v72 offset:34816
	ds_read_b64_tr_b16 v[130:131], v72 offset:35968
	ds_read_b64_tr_b16 v[132:133], v72 offset:37120
	ds_read_b64_tr_b16 v[134:135], v72 offset:38272
	ds_read_b128 v[164:167], v87
	ds_read_b128 v[168:171], v87 offset:1024
	s_waitcnt lgkmcnt(12)
	v_mfma_f32_16x16x32_bf16 v[172:175], v[112:115], v[96:99], 0
	ds_read_b64_tr_b16 v[136:137], v75 offset:17408
	ds_read_b64_tr_b16 v[138:139], v75 offset:21760
	s_waitcnt lgkmcnt(12)
	v_mfma_f32_16x16x32_bf16 v[172:175], v[116:119], v[100:103], v[172:175]
	ds_read_b64_tr_b16 v[140:141], v75 offset:17440
	ds_read_b64_tr_b16 v[142:143], v75 offset:21792
	s_waitcnt lgkmcnt(12)
	v_mfma_f32_16x16x32_bf16 v[172:175], v[120:123], v[104:107], v[172:175]
	ds_read_b64_tr_b16 v[144:145], v75 offset:26112
	ds_read_b64_tr_b16 v[146:147], v75 offset:30464
	s_waitcnt lgkmcnt(12)
	v_mfma_f32_16x16x32_bf16 v[172:175], v[124:127], v[108:111], v[172:175]
	ds_read_b64_tr_b16 v[148:149], v75 offset:26144
	ds_read_b64_tr_b16 v[150:151], v75 offset:30496
	s_waitcnt lgkmcnt(9)
	v_mfma_f32_16x16x32_bf16 v[172:175], v[128:131], v[164:167], v[172:175]
	s_waitcnt vmcnt(8)
	ds_write_b128 v62, v[22:25] offset:0
	ds_write_b128 v62, v[26:29] offset:8704
	ds_write_b128 v62, v[30:33] offset:17408
	ds_write_b128 v62, v[34:37] offset:26112
	ds_write_b64 v65, v[38:39] offset:34816
	v_add_f32_e32 v92, v40, v52
	v_mul_f32_e32 v92, 0x3fb8aa3b, v92
	v_exp_f32_e32 v92, v92
	v_mov_b32_e32 v52, v41
	ds_write_b32 v78, v92 offset:1024
	s_waitcnt lgkmcnt(14)
	s_cmp_eq_u32 s11, 0
	s_cbranch_scc1 .Lsc3_nopv1_3
	v_mfma_f32_16x16x32_bf16 v[172:175], v[132:135], v[168:171], v[172:175]
.Lsc3_nopv1_3:
	s_waitcnt lgkmcnt(12)
	v_mfma_f32_16x16x32_bf16 v[42:45], v[128:131], v[136:139], v[42:45]
	s_waitcnt lgkmcnt(10)
	v_mfma_f32_16x16x32_bf16 v[46:49], v[128:131], v[140:143], v[46:49]
	s_waitcnt lgkmcnt(8)
	v_mfma_f32_16x16x32_bf16 v[42:45], v[132:135], v[144:147], v[42:45]
	s_waitcnt lgkmcnt(6)
	v_mfma_f32_16x16x32_bf16 v[46:49], v[132:135], v[148:151], v[46:49]
	s_add_u32 s3, s34, 3
	s_cmp_lt_u32 s3, 4
	s_cselect_b32 s4, s16, s17
	s_mul_i32 s5, s3, s15
	s_add_i32 s4, s4, s5
	s_lshl_b32 s4, s4, 16
	s_add_u32 s64, s28, s4
	s_addc_u32 s65, s29, 0
	s_cmp_eq_u32 s34, 0
	s_cselect_b32 s64, s30, s64
	s_cselect_b32 s65, s31, s65
	v_cvt_pk_bf16_f32 v176, v172, v173
	v_cvt_pk_bf16_f32 v177, v174, v175
	global_store_dwordx2 v57, v[176:177], s[64:65]
	s_waitcnt lgkmcnt(0)
	ds_read_b32 v50, v79 offset:512
	ds_read_b32 v51, v79 offset:576
	ds_read_b128 v[96:99], v67 offset:0
	ds_read_b128 v[100:103], v67 offset:64
	ds_read_b128 v[104:107], v67 offset:128
	ds_read_b128 v[108:111], v67 offset:192
	s_cmp_eq_u32 s13, 0
	s_cbranch_scc1 .Lsc3_nox_4
	ds_read_b128 v[112:115], v70 offset:17408
	ds_read_b128 v[116:119], v70 offset:17472
	ds_read_b128 v[120:123], v70 offset:17536
	ds_read_b128 v[124:127], v70 offset:17600

.Lsc3_noy_4:
	s_add_u32 s3, s34, 7
	s_min_u32 s3, s3, 67
	s_cmp_lt_u32 s3, 4
	s_cselect_b32 s4, s16, s17
	s_mul_i32 s5, s3, s15
	s_add_i32 s4, s4, s5
	s_lshl_b32 s5, s4, 16
	s_lshl_b32 s4, s4, 11
	s_add_u32 s40, s18, s5
	s_addc_u32 s41, s19, 0
	s_add_u32 s42, s20, s5
	s_addc_u32 s43, s21, 0
	s_add_u32 s44, s22, s5
	s_addc_u32 s45, s23, 0
	s_add_u32 s46, s24, s4
	s_addc_u32 s47, s25, 0
	s_add_u32 s50, s26, s4
	s_addc_u32 s51, s27, 0
	global_load_dwordx4 v[22:25], v53, s[40:41]
	global_load_dwordx4 v[26:29], v54, s[40:41]
	global_load_dwordx4 v[30:33], v53, s[42:43]
	global_load_dwordx4 v[34:37], v54, s[42:43]
	global_load_dwordx2 v[38:39], v55, s[44:45]
	global_load_dword v40, v56, s[46:47]
	global_load_dword v41, v56, s[50:51]
	s_waitcnt lgkmcnt(0)
	s_cmp_eq_u32 s13, 0
	s_cbranch_scc1 .Lsc3_nox2_4
	v_mfma_f32_16x16x32_bf16 v[152:155], v[112:115], v[96:99], 0
	v_mfma_f32_16x16x32_bf16 v[152:155], v[116:119], v[100:103], v[152:155]
	v_mfma_f32_16x16x32_bf16 v[152:155], v[120:123], v[104:107], v[152:155]
	v_mfma_f32_16x16x32_bf16 v[152:155], v[124:127], v[108:111], v[152:155]

.Lsc3_noy3_4:
	ds_write_b64 v84, v[160:161]
	ds_write_b64 v84, v[162:163] offset:1024
	s_waitcnt lgkmcnt(0)
	s_barrier
	ds_read_b64_tr_b16 v[112:113], v82 offset:0
	ds_read_b64_tr_b16 v[114:115], v82 offset:288
	ds_read_b64_tr_b16 v[116:117], v82 offset:2304
	ds_read_b64_tr_b16 v[118:119], v82 offset:2592
	ds_read_b64_tr_b16 v[120:121], v82 offset:4608
	ds_read_b64_tr_b16 v[122:123], v82 offset:4896
	ds_read_b64_tr_b16 v[124:125], v82 offset:6912
	ds_read_b64_tr_b16 v[126:127], v82 offset:7200
	ds_read_b64_tr_b16 v[128:129], v73 offset:34816
	ds_read_b64_tr_b16 v[130:131], v73 offset:35968
	ds_read_b64_tr_b16 v[132:133], v73 offset:37120
	ds_read_b64_tr_b16 v[134:135], v73 offset:38272
	ds_read_b128 v[164:167], v86
	ds_read_b128 v[168:171], v86 offset:1024
	s_waitcnt lgkmcnt(12)
	v_mfma_f32_16x16x32_bf16 v[172:175], v[112:115], v[96:99], 0
	ds_read_b64_tr_b16 v[136:137], v76 offset:17408
	ds_read_b64_tr_b16 v[138:139], v76 offset:21760
	s_waitcnt lgkmcnt(12)
	v_mfma_f32_16x16x32_bf16 v[172:175], v[116:119], v[100:103], v[172:175]
	ds_read_b64_tr_b16 v[140:141], v76 offset:17440
	ds_read_b64_tr_b16 v[142:143], v76 offset:21792
	s_waitcnt lgkmcnt(12)
	v_mfma_f32_16x16x32_bf16 v[172:175], v[120:123], v[104:107], v[172:175]
	ds_read_b64_tr_b16 v[144:145], v76 offset:26112
	ds_read_b64_tr_b16 v[146:147], v76 offset:30464
	s_waitcnt lgkmcnt(12)
	v_mfma_f32_16x16x32_bf16 v[172:175], v[124:127], v[108:111], v[172:175]
	ds_read_b64_tr_b16 v[148:149], v76 offset:26144
	ds_read_b64_tr_b16 v[150:151], v76 offset:30496
	s_waitcnt lgkmcnt(9)
	v_mfma_f32_16x16x32_bf16 v[172:175], v[128:131], v[164:167], v[172:175]
	s_waitcnt vmcnt(8)
	ds_write_b128 v60, v[2:5] offset:0
	ds_write_b128 v60, v[6:9] offset:8704
	ds_write_b128 v60, v[10:13] offset:17408
	ds_write_b128 v60, v[14:17] offset:26112
	ds_write_b64 v63, v[18:19] offset:34816
	v_add_f32_e32 v92, v20, v52
	v_mul_f32_e32 v92, 0x3fb8aa3b, v92
	v_exp_f32_e32 v92, v92
	v_mov_b32_e32 v52, v21
	ds_write_b32 v78, v92 offset:0
	s_waitcnt lgkmcnt(14)
	s_cmp_eq_u32 s11, 0
	s_cbranch_scc1 .Lsc3_nopv1_4
	v_mfma_f32_16x16x32_bf16 v[172:175], v[132:135], v[168:171], v[172:175]
.Lsc3_nopv1_4:
	s_waitcnt lgkmcnt(12)
	v_mfma_f32_16x16x32_bf16 v[42:45], v[128:131], v[136:139], v[42:45]
	s_waitcnt lgkmcnt(10)
	v_mfma_f32_16x16x32_bf16 v[46:49], v[128:131], v[140:143], v[46:49]
	s_waitcnt lgkmcnt(8)
	v_mfma_f32_16x16x32_bf16 v[42:45], v[132:135], v[144:147], v[42:45]
	s_waitcnt lgkmcnt(6)
	v_mfma_f32_16x16x32_bf16 v[46:49], v[132:135], v[148:151], v[46:49]
	s_add_u32 s3, s34, 4
	s_cmp_lt_u32 s3, 4
	s_cselect_b32 s4, s16, s17
	s_mul_i32 s5, s3, s15
	s_add_i32 s4, s4, s5
	s_lshl_b32 s4, s4, 16
	s_add_u32 s64, s28, s4
	s_addc_u32 s65, s29, 0
	v_cvt_pk_bf16_f32 v176, v172, v173
	v_cvt_pk_bf16_f32 v177, v174, v175
	global_store_dwordx2 v57, v[176:177], s[64:65]
	s_waitcnt lgkmcnt(0)
	ds_read_b32 v50, v79 offset:1024
	ds_read_b32 v51, v79 offset:1088
	ds_read_b128 v[96:99], v68 offset:0
	ds_read_b128 v[100:103], v68 offset:64
	ds_read_b128 v[104:107], v68 offset:128
	ds_read_b128 v[108:111], v68 offset:192
	s_cmp_eq_u32 s13, 0
	s_cbranch_scc1 .Lsc3_nox_5
	ds_read_b128 v[112:115], v71 offset:17408
	ds_read_b128 v[116:119], v71 offset:17472
	ds_read_b128 v[120:123], v71 offset:17536
	ds_read_b128 v[124:127], v71 offset:17600

.Lsc3_noy_5:
	s_add_u32 s3, s34, 8
	s_min_u32 s3, s3, 67
	s_cmp_lt_u32 s3, 4
	s_cselect_b32 s4, s16, s17
	s_mul_i32 s5, s3, s15
	s_add_i32 s4, s4, s5
	s_lshl_b32 s5, s4, 16
	s_lshl_b32 s4, s4, 11
	s_add_u32 s40, s18, s5
	s_addc_u32 s41, s19, 0
	s_add_u32 s42, s20, s5
	s_addc_u32 s43, s21, 0
	s_add_u32 s44, s22, s5
	s_addc_u32 s45, s23, 0
	s_add_u32 s46, s24, s4
	s_addc_u32 s47, s25, 0
	s_add_u32 s50, s26, s4
	s_addc_u32 s51, s27, 0
	global_load_dwordx4 v[2:5], v53, s[40:41]
	global_load_dwordx4 v[6:9], v54, s[40:41]
	global_load_dwordx4 v[10:13], v53, s[42:43]
	global_load_dwordx4 v[14:17], v54, s[42:43]
	global_load_dwordx2 v[18:19], v55, s[44:45]
	global_load_dword v20, v56, s[46:47]
	global_load_dword v21, v56, s[50:51]
	s_waitcnt lgkmcnt(0)
	s_cmp_eq_u32 s13, 0
	s_cbranch_scc1 .Lsc3_nox2_5
	v_mfma_f32_16x16x32_bf16 v[152:155], v[112:115], v[96:99], 0
	v_mfma_f32_16x16x32_bf16 v[152:155], v[116:119], v[100:103], v[152:155]
	v_mfma_f32_16x16x32_bf16 v[152:155], v[120:123], v[104:107], v[152:155]
	v_mfma_f32_16x16x32_bf16 v[152:155], v[124:127], v[108:111], v[152:155]

; #define SCAN_BAR() asm volatile("s_waitcnt lgkmcnt(0)\n\ts_barrier" ::: "memory")
; __device__ void scan_phase(LAS unsigned char* lds, const Params& p) {
;     ...
;         SCAN_LOAD(0, k4A, q4A, v4A, rvA, tlA); SCAN_LOAD(1, k4B, q4B, v4B, rvB, tlB); SCAN_LOAD(2, k4C, q4C, v4C, rvC, tlC); SCAN_LOAD(3, k4D, q4D, v4D, rvD, tlD);
;         SCAN_STAGE(0, k4A, q4A, v4A, rvA, tlA); SCAN_LOAD(4, k4A, q4A, v4A, rvA, tlA);
;         SCAN_BAR();
; #pragma unroll 1
;         for (int n0 = 0; n0 < 68; n0 += 4) {
;             SCAN_STAGE(1, k4B, q4B, v4B, rvB, tlB); SCAN_LOAD(min(n0 + 5, 67), k4B, q4B, v4B, rvB, tlB); SCAN_MAT(0, n0); SCAN_BAR();
;             SCAN_STAGE(0, k4C, q4C, v4C, rvC, tlC); SCAN_LOAD(min(n0 + 6, 67), k4C, q4C, v4C, rvC, tlC); SCAN_MAT(1, n0 + 1); SCAN_BAR();
;             SCAN_STAGE(1, k4D, q4D, v4D, rvD, tlD); SCAN_LOAD(min(n0 + 7, 67), k4D, q4D, v4D, rvD, tlD); SCAN_MAT(0, n0 + 2); SCAN_BAR();
;             SCAN_STAGE(0, k4A, q4A, v4A, rvA, tlA); SCAN_LOAD(min(n0 + 8, 67), k4A, q4A, v4A, rvA, tlA); SCAN_MAT(1, n0 + 3); SCAN_BAR();
;         }
.Lsc3_noy3_5:
	ds_write_b64 v85, v[160:161]
	ds_write_b64 v85, v[162:163] offset:1024
	s_waitcnt lgkmcnt(0)
	s_barrier
	ds_read_b64_tr_b16 v[112:113], v83 offset:0
	ds_read_b64_tr_b16 v[114:115], v83 offset:288
	ds_read_b64_tr_b16 v[116:117], v83 offset:2304
	ds_read_b64_tr_b16 v[118:119], v83 offset:2592
	ds_read_b64_tr_b16 v[120:121], v83 offset:4608
	ds_read_b64_tr_b16 v[122:123], v83 offset:4896
	ds_read_b64_tr_b16 v[124:125], v83 offset:6912
	ds_read_b64_tr_b16 v[126:127], v83 offset:7200
	ds_read_b64_tr_b16 v[128:129], v74 offset:34816
	ds_read_b64_tr_b16 v[130:131], v74 offset:35968
	ds_read_b64_tr_b16 v[132:133], v74 offset:37120
	ds_read_b64_tr_b16 v[134:135], v74 offset:38272
	ds_read_b128 v[164:167], v87
	ds_read_b128 v[168:171], v87 offset:1024
	s_waitcnt lgkmcnt(12)
	v_mfma_f32_16x16x32_bf16 v[172:175], v[112:115], v[96:99], 0
	ds_read_b64_tr_b16 v[136:137], v77 offset:17408
	ds_read_b64_tr_b16 v[138:139], v77 offset:21760
	s_waitcnt lgkmcnt(12)
	v_mfma_f32_16x16x32_bf16 v[172:175], v[116:119], v[100:103], v[172:175]
	ds_read_b64_tr_b16 v[140:141], v77 offset:17440
	ds_read_b64_tr_b16 v[142:143], v77 offset:21792
	s_waitcnt lgkmcnt(12)
	v_mfma_f32_16x16x32_bf16 v[172:175], v[120:123], v[104:107], v[172:175]
	ds_read_b64_tr_b16 v[144:145], v77 offset:26112
	ds_read_b64_tr_b16 v[146:147], v77 offset:30464
	s_waitcnt lgkmcnt(12)
	v_mfma_f32_16x16x32_bf16 v[172:175], v[124:127], v[108:111], v[172:175]
	ds_read_b64_tr_b16 v[148:149], v77 offset:26144
	ds_read_b64_tr_b16 v[150:151], v77 offset:30496
	s_waitcnt lgkmcnt(9)
	v_mfma_f32_16x16x32_bf16 v[172:175], v[128:131], v[164:167], v[172:175]
	s_waitcnt vmcnt(8)
	ds_write_b128 v61, v[22:25] offset:0
	ds_write_b128 v61, v[26:29] offset:8704
	ds_write_b128 v61, v[30:33] offset:17408
	ds_write_b128 v61, v[34:37] offset:26112
	ds_write_b64 v64, v[38:39] offset:34816
	v_add_f32_e32 v92, v40, v52
	v_mul_f32_e32 v92, 0x3fb8aa3b, v92
	v_exp_f32_e32 v92, v92
	v_mov_b32_e32 v52, v41
	ds_write_b32 v78, v92 offset:512
	s_waitcnt lgkmcnt(14)
	s_cmp_eq_u32 s11, 0
	s_cbranch_scc1 .Lsc3_nopv1_5
	v_mfma_f32_16x16x32_bf16 v[172:175], v[132:135], v[168:171], v[172:175]
.Lsc3_nopv1_5:
	s_waitcnt lgkmcnt(12)
	v_mfma_f32_16x16x32_bf16 v[42:45], v[128:131], v[136:139], v[42:45]
	s_waitcnt lgkmcnt(10)
	v_mfma_f32_16x16x32_bf16 v[46:49], v[128:131], v[140:143], v[46:49]
	s_waitcnt lgkmcnt(8)
	v_mfma_f32_16x16x32_bf16 v[42:45], v[132:135], v[144:147], v[42:45]
	s_waitcnt lgkmcnt(6)
	v_mfma_f32_16x16x32_bf16 v[46:49], v[132:135], v[148:151], v[46:49]
	s_add_u32 s3, s34, 5
	s_cmp_lt_u32 s3, 4
	s_cselect_b32 s4, s16, s17
	s_mul_i32 s5, s3, s15
	s_add_i32 s4, s4, s5
	s_lshl_b32 s4, s4, 16
	s_add_u32 s64, s28, s4
	s_addc_u32 s65, s29, 0
	v_cvt_pk_bf16_f32 v176, v172, v173
	v_cvt_pk_bf16_f32 v177, v174, v175
	global_store_dwordx2 v57, v[176:177], s[64:65]
	s_waitcnt lgkmcnt(0)
	s_add_u32 s34, s34, 6
	s_cmp_lt_u32 s34, 66
	s_cbranch_scc1 .Lsc3_loop
	ds_read_b32 v50, v79 offset:0
	ds_read_b32 v51, v79 offset:64
	ds_read_b128 v[96:99], v66 offset:0
	ds_read_b128 v[100:103], v66 offset:64
	ds_read_b128 v[104:107], v66 offset:128
	ds_read_b128 v[108:111], v66 offset:192
	s_cmp_eq_u32 s13, 0
	s_cbranch_scc1 .Lsc3_nox_t0
	ds_read_b128 v[112:115], v69 offset:17408
	ds_read_b128 v[116:119], v69 offset:17472
	ds_read_b128 v[120:123], v69 offset:17536
	ds_read_b128 v[124:127], v69 offset:17600

.Lsc3_nopv1_t0:
	s_waitcnt lgkmcnt(12)
	v_mfma_f32_16x16x32_bf16 v[42:45], v[128:131], v[136:139], v[42:45]
	s_waitcnt lgkmcnt(10)
	v_mfma_f32_16x16x32_bf16 v[46:49], v[128:131], v[140:143], v[46:49]
	s_waitcnt lgkmcnt(8)
	v_mfma_f32_16x16x32_bf16 v[42:45], v[132:135], v[144:147], v[42:45]
	s_waitcnt lgkmcnt(6)
	v_mfma_f32_16x16x32_bf16 v[46:49], v[132:135], v[148:151], v[46:49]
	s_add_u32 s3, s34, 0
	s_cmp_lt_u32 s3, 4
	s_cselect_b32 s4, s16, s17
	s_mul_i32 s5, s3, s15
	s_add_i32 s4, s4, s5
	s_lshl_b32 s4, s4, 16
	s_add_u32 s64, s28, s4
	s_addc_u32 s65, s29, 0
	v_cvt_pk_bf16_f32 v176, v172, v173
	v_cvt_pk_bf16_f32 v177, v174, v175
	global_store_dwordx2 v57, v[176:177], s[64:65]
	s_waitcnt lgkmcnt(0)
	ds_read_b32 v50, v79 offset:512
	ds_read_b32 v51, v79 offset:576
	ds_read_b128 v[96:99], v67 offset:0
	ds_read_b128 v[100:103], v67 offset:64
	ds_read_b128 v[104:107], v67 offset:128
	ds_read_b128 v[108:111], v67 offset:192
	s_cmp_eq_u32 s13, 0
	s_cbranch_scc1 .Lsc3_nox_t1
	ds_read_b128 v[112:115], v70 offset:17408
	ds_read_b128 v[116:119], v70 offset:17472
	ds_read_b128 v[120:123], v70 offset:17536
	ds_read_b128 v[124:127], v70 offset:17600

; #define SCAN_BAR() asm volatile("s_waitcnt lgkmcnt(0)\n\ts_barrier" ::: "memory")
; __device__ void scan_phase(LAS unsigned char* lds, const Params& p) {
;     ...
;         SCAN_LOAD(0, k4A, q4A, v4A, rvA, tlA); SCAN_LOAD(1, k4B, q4B, v4B, rvB, tlB); SCAN_LOAD(2, k4C, q4C, v4C, rvC, tlC); SCAN_LOAD(3, k4D, q4D, v4D, rvD, tlD);
;         SCAN_STAGE(0, k4A, q4A, v4A, rvA, tlA); SCAN_LOAD(4, k4A, q4A, v4A, rvA, tlA);
;         SCAN_BAR();
; #pragma unroll 1
;         for (int n0 = 0; n0 < 68; n0 += 4) {
;             SCAN_STAGE(1, k4B, q4B, v4B, rvB, tlB); SCAN_LOAD(min(n0 + 5, 67), k4B, q4B, v4B, rvB, tlB); SCAN_MAT(0, n0); SCAN_BAR();
;             SCAN_STAGE(0, k4C, q4C, v4C, rvC, tlC); SCAN_LOAD(min(n0 + 6, 67), k4C, q4C, v4C, rvC, tlC); SCAN_MAT(1, n0 + 1); SCAN_BAR();
;             SCAN_STAGE(1, k4D, q4D, v4D, rvD, tlD); SCAN_LOAD(min(n0 + 7, 67), k4D, q4D, v4D, rvD, tlD); SCAN_MAT(0, n0 + 2); SCAN_BAR();
;             SCAN_STAGE(0, k4A, q4A, v4A, rvA, tlA); SCAN_LOAD(min(n0 + 8, 67), k4A, q4A, v4A, rvA, tlA); SCAN_MAT(1, n0 + 3); SCAN_BAR();
;         }
;     ...
;     }
.Lsc3_nopv1_t1:
	s_waitcnt lgkmcnt(12)
	v_mfma_f32_16x16x32_bf16 v[42:45], v[128:131], v[136:139], v[42:45]
	s_waitcnt lgkmcnt(10)
	v_mfma_f32_16x16x32_bf16 v[46:49], v[128:131], v[140:143], v[46:49]
	s_waitcnt lgkmcnt(8)
	v_mfma_f32_16x16x32_bf16 v[42:45], v[132:135], v[144:147], v[42:45]
	s_waitcnt lgkmcnt(6)
	v_mfma_f32_16x16x32_bf16 v[46:49], v[132:135], v[148:151], v[46:49]
	s_add_u32 s3, s34, 1
	s_cmp_lt_u32 s3, 4
	s_cselect_b32 s4, s16, s17
	s_mul_i32 s5, s3, s15
	s_add_i32 s4, s4, s5
	s_lshl_b32 s4, s4, 16
	s_add_u32 s64, s28, s4
	s_addc_u32 s65, s29, 0
	v_cvt_pk_bf16_f32 v176, v172, v173
	v_cvt_pk_bf16_f32 v177, v174, v175
	global_store_dwordx2 v57, v[176:177], s[64:65]
	s_waitcnt lgkmcnt(0)
	s_barrier
	s_add_u32 s9, s9, s35
	s_cmp_lt_u32 s9, 0x100
	s_cbranch_scc1 .Lsc3_item

; #define LAS __attribute__((address_space(3)))
; __global__ void __launch_bounds__(NTHR, 2) hymba_fwd(Params p) {
;     extern __shared__ __attribute__((aligned(16))) unsigned char lds_raw[];
;     LAS unsigned char* lds = (LAS unsigned char*)lds_raw;
	.amdhsa_kernel _Z9hymba_fwd6Params
		.amdhsa_group_segment_fixed_size 25600
		.amdhsa_private_segment_fixed_size 0
		.amdhsa_kernarg_size 408
		.amdhsa_user_sgpr_count 2
		.amdhsa_user_sgpr_dispatch_ptr 0
		.amdhsa_user_sgpr_queue_ptr 0
		.amdhsa_user_sgpr_kernarg_segment_ptr 1
		.amdhsa_user_sgpr_dispatch_id 0
		.amdhsa_user_sgpr_kernarg_preload_length 0
		.amdhsa_user_sgpr_kernarg_preload_offset 0
		.amdhsa_user_sgpr_private_segment_size 0
		.amdhsa_uses_dynamic_stack 0
		.amdhsa_enable_private_segment 0
		.amdhsa_system_sgpr_workgroup_id_x 1
		.amdhsa_system_sgpr_workgroup_id_y 0
		.amdhsa_system_sgpr_workgroup_id_z 0
		.amdhsa_system_sgpr_workgroup_info 0
		.amdhsa_system_vgpr_workitem_id 0
		.amdhsa_next_free_vgpr 231
		.amdhsa_next_free_sgpr 100
		.amdhsa_accum_offset 232
		.amdhsa_reserve_vcc 1
		.amdhsa_float_round_mode_32 0
		.amdhsa_float_round_mode_16_64 0
		.amdhsa_float_denorm_mode_32 3
		.amdhsa_float_denorm_mode_16_64 3
		.amdhsa_dx10_clamp 1
		.amdhsa_ieee_mode 1
		.amdhsa_fp16_overflow 0
		.amdhsa_tg_split 0
		.amdhsa_exception_fp_ieee_invalid_op 0
		.amdhsa_exception_fp_denorm_src 0
		.amdhsa_exception_fp_ieee_div_zero 0
		.amdhsa_exception_fp_ieee_overflow 0
		.amdhsa_exception_fp_ieee_underflow 0
		.amdhsa_exception_fp_ieee_inexact 0
		.amdhsa_exception_int_div_zero 0
	.end_amdhsa_kernel

; #define LAS __attribute__((address_space(3)))
; __global__ void __launch_bounds__(NTHR, 2) hymba_fwd(Params p) {
;     extern __shared__ __attribute__((aligned(16))) unsigned char lds_raw[];
;     LAS unsigned char* lds = (LAS unsigned char*)lds_raw;
amdhsa.kernels:
  - .agpr_count:     0
    .args:
      - .offset:         0
        .size:           152
        .value_kind:     by_value
      - .offset:         152
        .size:           4
        .value_kind:     hidden_block_count_x
      - .offset:         156
        .size:           4
        .value_kind:     hidden_block_count_y
      - .offset:         160
        .size:           4
        .value_kind:     hidden_block_count_z
      - .offset:         164
        .size:           2
        .value_kind:     hidden_group_size_x
      - .offset:         166
        .size:           2
        .value_kind:     hidden_group_size_y
      - .offset:         168
        .size:           2
        .value_kind:     hidden_group_size_z
      - .offset:         170
        .size:           2
        .value_kind:     hidden_remainder_x
      - .offset:         172
        .size:           2
        .value_kind:     hidden_remainder_y
      - .offset:         174
        .size:           2
        .value_kind:     hidden_remainder_z
      - .offset:         192
        .size:           8
        .value_kind:     hidden_global_offset_x
      - .offset:         200
        .size:           8
        .value_kind:     hidden_global_offset_y
      - .offset:         208
        .size:           8
        .value_kind:     hidden_global_offset_z
      - .offset:         216
        .size:           2
        .value_kind:     hidden_grid_dims
      - .offset:         272
        .size:           4
        .value_kind:     hidden_dynamic_lds_size
    .group_segment_fixed_size: 25600
    .kernarg_segment_align: 8
    .kernarg_segment_size: 408
    .language:       OpenCL C
    .language_version:
      - 2
      - 0
    .max_flat_workgroup_size: 512
    .name:           _Z9hymba_fwd6Params
    .private_segment_fixed_size: 0
    .sgpr_count:     106
    .sgpr_spill_count: 4
    .symbol:         _Z9hymba_fwd6Params.kd
    .uniform_work_group_size: 1
    .uses_dynamic_stack: false
    .vgpr_count:     231
    .vgpr_spill_count: 0
    .wavefront_size: 64
